# P7 stage 1b: partner top-16 merged by max-against-reversed + bitonic clean-up instead of 16 insertions
# speedup vs baseline: 1.0350x; 1.0085x over previous
; #define LAS __attribute__((address_space(3)))
; __device__ __forceinline__ unsigned umed3(unsigned a, unsigned b, unsigned c) { unsigned r; asm("v_med3_u32 %0, %1, %2, %3" : "=v"(r) : "v"(a), "v"(b), "v"(c)); return r; }
; __global__ void __launch_bounds__(NTHR, 2) fwd_megakernel(Args a) {
;     ...
;                 if (hf == 0) {
; #pragma unroll
;                     for (int q = 0; q < 4; ++q) { const u32x4 o = *(const LAS u32x4*)(KX + row * 16 + 4 * q);
; #pragma unroll
;                         for (int c = 0; c < 4; ++c) { const unsigned uk = o[c];
; #pragma unroll
;                             for (int j = 15; j >= 1; --j) v[j] = umed3(v[j - 1], v[j], uk);
;                             v[0] = v[0] > uk ? v[0] : uk; } }
;                     u32x4 iw;
; #pragma unroll
;                     for (int q = 0; q < 4; ++q) { unsigned w = 0;
; #pragma unroll
;                         for (int j = 0; j < 4; ++j) w |= (127u - (v[4 * q + j] & 127u)) << (8 * j);
;                         iw[q] = w; }
;                     *(LAS u32x4*)(TOPI + row * 16) = iw;
.LBB0_802:
	s_andn2_saveexec_b64 s[0:1], s[14:15]
	s_cbranch_execz .LBB0_804
	ds_read_b128 v[28:31], v87
	ds_read_b128 v[24:27], v87 offset:16
	ds_read_b128 v[20:23], v87 offset:32
	ds_read_b128 v[16:19], v87 offset:48
	s_waitcnt lgkmcnt(0)
	v_max_u32_e32 v0, v0, v19
	v_max_u32_e32 v1, v1, v18
	v_max_u32_e32 v2, v2, v17
	v_max_u32_e32 v3, v3, v16
	v_max_u32_e32 v4, v4, v23
	v_max_u32_e32 v5, v5, v22
	v_max_u32_e32 v6, v6, v21
	v_max_u32_e32 v7, v7, v20
	v_max_u32_e32 v8, v8, v27
	v_max_u32_e32 v9, v9, v26
	v_max_u32_e32 v10, v10, v25
	v_max_u32_e32 v11, v11, v24
	v_max_u32_e32 v12, v12, v31
	v_max_u32_e32 v13, v13, v30
	v_max_u32_e32 v14, v14, v29
	v_max_u32_e32 v15, v15, v28
	v_max_u32_e32 v16, v0, v8
	v_min_u32_e32 v8, v0, v8
	v_mov_b32_e32 v0, v16
	v_max_u32_e32 v17, v1, v9
	v_min_u32_e32 v9, v1, v9
	v_mov_b32_e32 v1, v17
	v_max_u32_e32 v18, v2, v10
	v_min_u32_e32 v10, v2, v10
	v_mov_b32_e32 v2, v18
	v_max_u32_e32 v19, v3, v11
	v_min_u32_e32 v11, v3, v11
	v_mov_b32_e32 v3, v19
	v_max_u32_e32 v20, v4, v12
	v_min_u32_e32 v12, v4, v12
	v_mov_b32_e32 v4, v20
	v_max_u32_e32 v21, v5, v13
	v_min_u32_e32 v13, v5, v13
	v_mov_b32_e32 v5, v21
	v_max_u32_e32 v22, v6, v14
	v_min_u32_e32 v14, v6, v14
	v_mov_b32_e32 v6, v22
	v_max_u32_e32 v23, v7, v15
	v_min_u32_e32 v15, v7, v15
	v_mov_b32_e32 v7, v23
	v_max_u32_e32 v16, v0, v4
	v_min_u32_e32 v4, v0, v4
	v_mov_b32_e32 v0, v16
	v_max_u32_e32 v17, v1, v5
	v_min_u32_e32 v5, v1, v5
	v_mov_b32_e32 v1, v17
	v_max_u32_e32 v18, v2, v6
	v_min_u32_e32 v6, v2, v6
	v_mov_b32_e32 v2, v18
	v_max_u32_e32 v19, v3, v7
	v_min_u32_e32 v7, v3, v7
	v_mov_b32_e32 v3, v19
	v_max_u32_e32 v20, v8, v12
	v_min_u32_e32 v12, v8, v12
	v_mov_b32_e32 v8, v20
	v_max_u32_e32 v21, v9, v13
	v_min_u32_e32 v13, v9, v13
	v_mov_b32_e32 v9, v21
	v_max_u32_e32 v22, v10, v14
	v_min_u32_e32 v14, v10, v14
	v_mov_b32_e32 v10, v22
	v_max_u32_e32 v23, v11, v15
	v_min_u32_e32 v15, v11, v15
	v_mov_b32_e32 v11, v23
	v_max_u32_e32 v16, v0, v2
	v_min_u32_e32 v2, v0, v2
	v_mov_b32_e32 v0, v16
	v_max_u32_e32 v17, v1, v3
	v_min_u32_e32 v3, v1, v3
	v_mov_b32_e32 v1, v17
	v_max_u32_e32 v18, v4, v6
	v_min_u32_e32 v6, v4, v6
	v_mov_b32_e32 v4, v18
	v_max_u32_e32 v19, v5, v7
	v_min_u32_e32 v7, v5, v7
	v_mov_b32_e32 v5, v19
	v_max_u32_e32 v20, v8, v10
	v_min_u32_e32 v10, v8, v10
	v_mov_b32_e32 v8, v20
	v_max_u32_e32 v21, v9, v11
	v_min_u32_e32 v11, v9, v11
	v_mov_b32_e32 v9, v21
	v_max_u32_e32 v22, v12, v14
	v_min_u32_e32 v14, v12, v14
	v_mov_b32_e32 v12, v22
	v_max_u32_e32 v23, v13, v15
	v_min_u32_e32 v15, v13, v15
	v_mov_b32_e32 v13, v23
	v_max_u32_e32 v16, v0, v1
	v_min_u32_e32 v1, v0, v1
	v_mov_b32_e32 v0, v16
	v_max_u32_e32 v17, v2, v3
	v_min_u32_e32 v3, v2, v3
	v_mov_b32_e32 v2, v17
	v_max_u32_e32 v18, v4, v5
	v_min_u32_e32 v5, v4, v5
	v_mov_b32_e32 v4, v18
	v_max_u32_e32 v19, v6, v7
	v_min_u32_e32 v7, v6, v7
	v_mov_b32_e32 v6, v19
	v_max_u32_e32 v20, v8, v9
	v_min_u32_e32 v9, v8, v9
	v_mov_b32_e32 v8, v20
	v_max_u32_e32 v21, v10, v11
	v_min_u32_e32 v11, v10, v11
	v_mov_b32_e32 v10, v21
	v_max_u32_e32 v22, v12, v13
	v_min_u32_e32 v13, v12, v13
	v_mov_b32_e32 v12, v22
	v_max_u32_e32 v23, v14, v15
	v_min_u32_e32 v15, v14, v15
	v_mov_b32_e32 v14, v23
	v_lshlrev_b32_e32 v1, 8, v1
	v_lshlrev_b32_e32 v2, 16, v2
	v_and_b32_e32 v0, 0x7f, v0
	v_and_b32_e32 v1, 0x7f00, v1
	v_and_b32_e32 v2, 0x7f0000, v2
	v_or3_b32 v0, v0, v1, v2
	v_lshlrev_b32_e32 v1, 24, v3
	v_and_b32_e32 v1, 0x7f000000, v1
	v_lshlrev_b32_e32 v2, 8, v5
	v_lshlrev_b32_e32 v3, 16, v6
	v_bitop3_b32 v0, v0, s71, v1 bitop3:0x36
	v_and_b32_e32 v1, 0x7f, v4
	v_and_b32_e32 v2, 0x7f00, v2
	v_and_b32_e32 v3, 0x7f0000, v3
	v_or3_b32 v1, v1, v2, v3
	v_lshlrev_b32_e32 v2, 24, v7
	v_and_b32_e32 v2, 0x7f000000, v2
	v_lshlrev_b32_e32 v3, 8, v9
	v_lshlrev_b32_e32 v4, 16, v10
	v_bitop3_b32 v1, v1, s71, v2 bitop3:0x36
	v_and_b32_e32 v2, 0x7f, v8
	v_and_b32_e32 v3, 0x7f00, v3
	v_and_b32_e32 v4, 0x7f0000, v4
	v_or3_b32 v2, v2, v3, v4
	v_lshlrev_b32_e32 v3, 24, v11
	v_and_b32_e32 v3, 0x7f000000, v3
	v_lshlrev_b32_e32 v4, 8, v13
	v_lshlrev_b32_e32 v5, 16, v14
	v_bitop3_b32 v2, v2, s71, v3 bitop3:0x36
	v_and_b32_e32 v3, 0x7f, v12
	v_and_b32_e32 v4, 0x7f00, v4
	v_and_b32_e32 v5, 0x7f0000, v5
	v_or3_b32 v3, v3, v4, v5
	v_lshlrev_b32_e32 v4, 24, v15
	v_and_b32_e32 v4, 0x7f000000, v4
	v_bitop3_b32 v3, v3, s71, v4 bitop3:0x36
	ds_write_b128 v80, v[0:3]
